# P9 on a 256-WG grid: static first-round task index (no 1024-atomic burst on the queue word), compressed queue no longer polled
# speedup vs baseline: 1.0444x; 1.0036x over previous
.LBB0_1059:
	s_cmp_lt_i32 s74, 10
	s_cselect_b64 s[0:1], -1, 0
	s_and_b64 s[40:41], s[0:1], s[2:3]
	s_andn2_b64 vcc, exec, s[40:41]
	s_cbranch_vccnz .LBB0_1203
	s_mov_b32 s101, 0
	s_mov_b32 s98, 0
	v_readlane_b32 s0, v254, 23
	v_lshlrev_b32_e32 v1, 2, v199
	v_readlane_b32 s6, v254, 29
	v_readlane_b32 s7, v254, 30
	v_readlane_b32 s12, v254, 35
	v_readlane_b32 s13, v254, 36
	s_nop 2
	global_load_dword v2, v1, s[6:7]
	s_waitcnt lgkmcnt(0)
	global_load_dword v3, v1, s[12:13]
	global_load_dword v4, v1, s[12:13] offset:512
	v_mbcnt_lo_u32_b32 v1, -1, 0
	v_mbcnt_hi_u32_b32 v1, -1, v1
	v_and_b32_e32 v5, 64, v1
	v_xor_b32_e32 v6, 1, v1
	v_add_u32_e32 v5, 64, v5
	v_cmp_lt_i32_e32 vcc, v6, v5
	v_xor_b32_e32 v7, 2, v1
	v_xor_b32_e32 v8, 4, v1
	v_cndmask_b32_e32 v6, v1, v6, vcc
	v_lshlrev_b32_e32 v6, 2, v6
	v_cmp_lt_i32_e32 vcc, v7, v5
	v_xor_b32_e32 v9, 8, v1
	v_xor_b32_e32 v10, 16, v1
	v_cndmask_b32_e32 v7, v1, v7, vcc
	v_lshlrev_b32_e32 v7, 2, v7
	v_cmp_lt_i32_e32 vcc, v8, v5
	v_xor_b32_e32 v11, 32, v1
	s_add_u32 s46, s72, 0x70000
	v_cndmask_b32_e32 v8, v1, v8, vcc
	v_lshlrev_b32_e32 v8, 2, v8
	v_cmp_lt_i32_e32 vcc, v9, v5
	s_addc_u32 s47, s73, 0
	s_cmpk_lt_u32 s76, 0x100
	v_cndmask_b32_e32 v9, v1, v9, vcc
	v_lshlrev_b32_e32 v9, 2, v9
	v_cmp_lt_i32_e32 vcc, v10, v5
	v_readlane_b32 s2, v254, 25
	v_readlane_b32 s3, v254, 26
	s_cselect_b64 s[50:51], -1, 0
	s_cmpk_gt_u32 s76, 0xff
	v_readlane_b32 s4, v254, 27
	s_cselect_b64 s[2:3], -1, 0
	s_mov_b32 s4, -1
	v_readlane_b32 s1, v254, 24
	v_readlane_b32 s5, v254, 28
	v_readlane_b32 s8, v254, 31
	v_readlane_b32 s9, v254, 32
	v_readlane_b32 s10, v254, 33
	v_readlane_b32 s11, v254, 34
	v_readlane_b32 s14, v254, 37
	v_readlane_b32 s15, v254, 38
	s_waitcnt vmcnt(0)
	v_and_b32_e32 v12, 0x7fffffff, v2
	v_and_b32_e32 v13, 0x7fffffff, v3
	v_and_b32_e32 v14, 0x7fffffff, v4
	ds_bpermute_b32 v12, v6, v12
	ds_bpermute_b32 v13, v6, v13
	ds_bpermute_b32 v6, v6, v14
	v_max_f32_e64 v2, |v2|, |v2|
	v_max_f32_e64 v3, |v3|, |v3|
	v_max_f32_e64 v4, |v4|, |v4|
	s_waitcnt lgkmcnt(2)
	v_max_f32_e32 v12, v12, v12
	s_waitcnt lgkmcnt(1)
	v_max_f32_e32 v13, v13, v13
	s_waitcnt lgkmcnt(0)
	v_max_f32_e32 v6, v6, v6
	v_max_f32_e32 v2, v2, v12
	v_max_f32_e32 v3, v3, v13
	v_max_f32_e32 v4, v4, v6
	ds_bpermute_b32 v6, v7, v2
	ds_bpermute_b32 v12, v7, v3
	ds_bpermute_b32 v7, v7, v4
	s_waitcnt lgkmcnt(2)
	v_max_f32_e32 v6, v6, v6
	s_waitcnt lgkmcnt(1)
	v_max_f32_e32 v12, v12, v12
	s_waitcnt lgkmcnt(0)
	v_max_f32_e32 v7, v7, v7
	v_max_f32_e32 v2, v2, v6
	v_max_f32_e32 v3, v3, v12
	v_max_f32_e32 v4, v4, v7
	ds_bpermute_b32 v6, v8, v2
	ds_bpermute_b32 v7, v8, v3
	ds_bpermute_b32 v8, v8, v4
	s_waitcnt lgkmcnt(2)
	v_max_f32_e32 v6, v6, v6
	s_waitcnt lgkmcnt(1)
	v_max_f32_e32 v7, v7, v7
	s_waitcnt lgkmcnt(0)
	v_max_f32_e32 v8, v8, v8
	v_max_f32_e32 v2, v2, v6
	v_max_f32_e32 v3, v3, v7
	v_max_f32_e32 v4, v4, v8
	ds_bpermute_b32 v6, v9, v2
	ds_bpermute_b32 v7, v9, v3
	ds_bpermute_b32 v8, v9, v4
	v_cndmask_b32_e32 v9, v1, v10, vcc
	v_lshlrev_b32_e32 v9, 2, v9
	s_waitcnt lgkmcnt(2)
	v_max_f32_e32 v6, v6, v6
	s_waitcnt lgkmcnt(1)
	v_max_f32_e32 v7, v7, v7
	s_waitcnt lgkmcnt(0)
	v_max_f32_e32 v8, v8, v8
	v_max_f32_e32 v2, v2, v6
	v_max_f32_e32 v3, v3, v7
	v_max_f32_e32 v4, v4, v8
	ds_bpermute_b32 v6, v9, v2
	ds_bpermute_b32 v7, v9, v3
	ds_bpermute_b32 v8, v9, v4
	v_cmp_lt_i32_e32 vcc, v11, v5
	s_waitcnt lgkmcnt(1)
	v_max_f32_e32 v5, v7, v7
	v_cndmask_b32_e32 v1, v1, v11, vcc
	v_lshlrev_b32_e32 v207, 2, v1
	v_max_f32_e32 v1, v6, v6
	s_waitcnt lgkmcnt(0)
	v_max_f32_e32 v6, v8, v8
	v_max_f32_e32 v2, v2, v1
	v_max_f32_e32 v1, v3, v5
	v_max_f32_e32 v181, v4, v6
	ds_bpermute_b32 v4, v207, v2
	ds_bpermute_b32 v3, v207, v1
	ds_bpermute_b32 v204, v207, v181
	s_and_b64 vcc, exec, s[2:3]
	s_cbranch_vccnz .LBB0_1068
	v_cmp_eq_u32_e32 vcc, 0, v199
	s_cmpk_eq_i32 s33, 0x100
	s_cbranch_scc1 .Lp9_static_idx
	v_mov_b32_e32 v5, -1
	s_and_saveexec_b64 s[4:5], vcc
	s_cbranch_execz .LBB0_1065
	s_mov_b64 s[8:9], exec
	v_mbcnt_lo_u32_b32 v5, s8, 0
	v_mbcnt_hi_u32_b32 v5, s9, v5
	v_cmp_eq_u32_e64 s[0:1], 0, v5
	s_and_saveexec_b64 s[6:7], s[0:1]
	s_cbranch_execz .LBB0_1064
	s_bcnt1_i32_b64 s0, s[8:9]
	v_mov_b32_e32 v6, 0
	v_mov_b32_e32 v7, s0
	global_atomic_add v6, v6, v7, s[46:47] sc0

.Lp9_static_idx:
	s_lshr_b32 s4, s80, 1
	s_lshl_b32 s4, s4, 2
	s_add_i32 s4, s4, s77
	s_lshl_b32 s4, s4, 1
	s_and_b32 s5, s80, 1
	s_or_b32 s4, s4, s5

.LBB0_1133:
	s_cmpk_lg_i32 s33, 0x100
	s_cbranch_scc1 .Lp9_q_generic
	s_cmpk_eq_u32 s55, 0x400
	s_cbranch_scc0 .Lp9_q_generic
	s_mov_b64 s[0:1], -1
	s_branch .LBB0_1132
